# code placement: peeled first-iteration copies also pinned to 64B (stacked on v17)
# baseline (speedup 1.0000x reference)
; #define PG8_STAGE(bufoff, gbase, voff) do { _Pragma("unroll") for (int _i = 0; _i < 2; ++_i) \
;         __builtin_amdgcn_global_load_lds((const unsigned*)((const char*)(gbase) + (voff)[_i]), (LAS unsigned*)(lds + (bufoff) + ldsw + _i * 8192), 16, 0, 0); } while (0)
; #define PG8_LDA(dst, b, h) do { _Pragma("unroll") for (int m = 0; m < 4; ++m) _Pragma("unroll") for (int k = 0; k < 2; ++k) dst[m][k] = *(const LAS bf16x8*)(lds + PG8_SA(b, h) + aoff + m * 2048 + k * 1024); } while (0)
; #define PG8_LDB(dst, b, h) do { _Pragma("unroll") for (int n = 0; n < 2; ++n) _Pragma("unroll") for (int k = 0; k < 2; ++k) dst[n][k] = *(const LAS bf16x8*)(lds + PG8_SB(b, h) + boff + n * 2048 + k * 1024); } while (0)
; #define PG8_MMA(ai, bj, At, Bt) do { __builtin_amdgcn_s_setprio(1); _Pragma("unroll") for (int m = 0; m < 4; ++m) _Pragma("unroll") for (int n = 0; n < 2; ++n) _Pragma("unroll") for (int k = 0; k < 2; ++k) \
;         acc[ai][bj][m][n] = __builtin_amdgcn_mfma_f32_16x16x32_bf16(Bt[n][k], At[m][k], acc[ai][bj][m][n], 0, 0, 0); __builtin_amdgcn_s_setprio(0); } while (0)
; #define PG8_WAIT_L(n) asm volatile("s_waitcnt lgkmcnt(" #n ")" ::: "memory")
; template <class Epi>
; DI void gemm_phase(int wv, LAS unsigned char* lds, const GemmD g, const Epi& E) {
;     ...
;         const bool has_next = S.next(ui + 1, nxt);
;         const char* nA = has_next ? (const char*)g.A + (size_t)nxt.pm * 256 * g.lda * 2 : cA; const char* nB = has_next ? (const char*)g.Bt + PG8_BROW(nxt.pn) * (size_t)g.ldb * 2 : cB;
;         for (int t = 0; t < nt; t += 2) {
;             const bool last = (t == nt - 2);
;             const char* a1 = cA + (size_t)(t + 1) * kstep;
;             const char* a2 = last ? nA : cA + (size_t)(t + 2) * kstep; const char* b2 = last ? nB : cB + (size_t)(t + 2) * kstep;
;             const char* a3 = a2 + kstep; const char* b3 = b2 + kstep;
;             PG8_LDB(B0, 0, 0); PG8_SCHED; PG8_LDA(At, 0, 0); PG8_STAGE(PG8_SA(1, 1), a1 + hstepA, voffA);
;             PG8_WAIT_L(8); PG8_BAR; PG8_WAIT_L(0); PG8_MMA(0, 0, At, B0); PG8_BAR; PG8_SCHED;
;             PG8_LDB(B1, 0, 1); PG8_STAGE(PG8_SB(0, 0), b2, voffB);
;             PG8_BAR; PG8_WAIT_L(0); PG8_MMA(0, 1, At, B1); PG8_BAR;
;             PG8_LDA(At, 0, 1); PG8_STAGE(PG8_SA(0, 0), a2, voffA);
;             PG8_BAR; PG8_WAIT_L(0); PG8_MMA(1, 0, At, B0); PG8_BAR; PG8_SCHED;
.LBB0_98:
	s_ashr_i32 s17, s16, 31
	s_lshl_b64 s[20:21], s[16:17], 19
	s_add_u32 s20, s6, s20
	s_addc_u32 s21, s7, s21
	s_and_b64 s[4:5], s[4:5], exec
	s_cselect_b32 s17, s21, s25
	s_cselect_b32 vcc_lo, s20, s24
	s_add_u32 s4, s24, 0x40080
	s_addc_u32 s5, s25, 0
	s_add_u32 vcc_hi, s22, 0x100
	s_addc_u32 s75, s23, 0
	s_mov_b32 s95, -2
	.p2align 6
	s_add_u32 s22, s4, 0xfffc0080
	s_addc_u32 s23, s5, -1
	s_add_i32 s3, 0, 0x10000
	v_add_u32_e32 v156, s3, v141
	ds_read_b128 v[144:147], v156
	ds_read_b128 v[148:151], v156 offset:1024
	ds_read_b128 v[152:155], v156 offset:2048
	ds_read_b128 v[156:159], v156 offset:3072
	s_cmp_eq_u32 s95, 12
	s_cselect_b32 s23, s17, s23
	s_cselect_b32 s22, vcc_lo, s22
	s_cselect_b32 s25, s19, s75
	s_cselect_b32 s24, s18, vcc_hi
	v_lshl_add_u64 v[164:165], s[4:5], 0, v[136:137]
	s_add_i32 m0, s15, 0xc000
	ds_read_b128 v[160:163], v143
	ds_read_b128 v[176:179], v143 offset:1024
	ds_read_b128 v[180:183], v143 offset:2048
	ds_read_b128 v[184:187], v143 offset:3072
	ds_read_b128 v[188:191], v143 offset:4096
	ds_read_b128 v[192:195], v143 offset:5120
	ds_read_b128 v[196:199], v143 offset:6144
	ds_read_b128 v[200:203], v143 offset:7168
	global_load_lds_dwordx4 v[164:165], off
	v_lshl_add_u64 v[164:165], s[4:5], 0, v[138:139]
	s_add_i32 m0, s15, 0xe000
	s_nop 0
	global_load_lds_dwordx4 v[164:165], off
	s_waitcnt lgkmcnt(8)
	s_barrier
	s_waitcnt lgkmcnt(0)
	s_waitcnt lgkmcnt(0)
	v_mfma_f32_16x16x32_bf16 v[126:129], v[144:147], v[160:163], 0
	v_mfma_f32_16x16x32_bf16 v[122:125], v[152:155], v[160:163], 0
	v_mfma_f32_16x16x32_bf16 v[118:121], v[144:147], v[180:183], 0
	v_mfma_f32_16x16x32_bf16 v[114:117], v[152:155], v[180:183], 0
	v_mfma_f32_16x16x32_bf16 v[102:105], v[144:147], v[188:191], 0
	v_mfma_f32_16x16x32_bf16 v[98:101], v[152:155], v[188:191], 0
	v_mfma_f32_16x16x32_bf16 v[86:89], v[144:147], v[196:199], 0
	v_mfma_f32_16x16x32_bf16 v[82:85], v[152:155], v[196:199], 0
	v_mfma_f32_16x16x32_bf16 v[126:129], v[148:151], v[176:179], v[126:129]
	v_mfma_f32_16x16x32_bf16 v[122:125], v[156:159], v[176:179], v[122:125]
	v_mfma_f32_16x16x32_bf16 v[118:121], v[148:151], v[184:187], v[118:121]
	v_mfma_f32_16x16x32_bf16 v[114:117], v[156:159], v[184:187], v[114:117]
	v_mfma_f32_16x16x32_bf16 v[102:105], v[148:151], v[192:195], v[102:105]
	v_mfma_f32_16x16x32_bf16 v[98:101], v[156:159], v[192:195], v[98:101]
	v_mfma_f32_16x16x32_bf16 v[86:89], v[148:151], v[200:203], v[86:89]
	v_mfma_f32_16x16x32_bf16 v[82:85], v[156:159], v[200:203], v[82:85]
	s_barrier
	s_add_i32 s2, 0, 0x14000
	v_add_u32_e32 v164, s2, v141
	s_add_i32 s3, s3, s37
	ds_read_b128 v[204:207], v164
	ds_read_b128 v[208:211], v164 offset:1024
	ds_read_b128 v[212:215], v164 offset:2048
	ds_read_b128 v[216:219], v164 offset:3072
	v_lshl_add_u64 v[164:165], s[24:25], 0, v[0:1]
	s_mov_b32 m0, s3
	v_lshl_add_u64 v[168:169], s[24:25], 0, v[130:131]
	global_load_lds_dwordx4 v[164:165], off
	s_add_i32 m0, s3, 0x2000
	s_nop 0
	global_load_lds_dwordx4 v[168:169], off
	s_barrier
	s_waitcnt lgkmcnt(0)
	s_waitcnt lgkmcnt(0)
	v_mfma_f32_16x16x32_bf16 v[110:113], v[204:207], v[160:163], 0
	v_mfma_f32_16x16x32_bf16 v[106:109], v[212:215], v[160:163], 0
	v_mfma_f32_16x16x32_bf16 v[94:97], v[204:207], v[180:183], 0
	v_mfma_f32_16x16x32_bf16 v[90:93], v[212:215], v[180:183], 0
	v_mfma_f32_16x16x32_bf16 v[78:81], v[204:207], v[188:191], 0
	v_mfma_f32_16x16x32_bf16 v[74:77], v[212:215], v[188:191], 0
	v_mfma_f32_16x16x32_bf16 v[70:73], v[204:207], v[196:199], 0
	v_mfma_f32_16x16x32_bf16 v[66:69], v[212:215], v[196:199], 0
	v_mfma_f32_16x16x32_bf16 v[110:113], v[208:211], v[176:179], v[110:113]
	v_mfma_f32_16x16x32_bf16 v[106:109], v[216:219], v[176:179], v[106:109]
	v_mfma_f32_16x16x32_bf16 v[94:97], v[208:211], v[184:187], v[94:97]
	v_mfma_f32_16x16x32_bf16 v[90:93], v[216:219], v[184:187], v[90:93]
	v_mfma_f32_16x16x32_bf16 v[78:81], v[208:211], v[192:195], v[78:81]
	v_mfma_f32_16x16x32_bf16 v[74:77], v[216:219], v[192:195], v[74:77]
	v_mfma_f32_16x16x32_bf16 v[70:73], v[208:211], v[200:203], v[70:73]
	v_mfma_f32_16x16x32_bf16 v[66:69], v[216:219], v[200:203], v[66:69]
	s_mov_b32 m0, s15
	v_lshl_add_u64 v[170:171], s[22:23], 0, v[134:135]
	s_barrier
	ds_read_b128 v[160:163], v143 offset:16384
	ds_read_b128 v[176:179], v143 offset:17408
	ds_read_b128 v[180:183], v143 offset:18432
	ds_read_b128 v[184:187], v143 offset:19456
	ds_read_b128 v[188:191], v143 offset:20480
	ds_read_b128 v[192:195], v143 offset:21504
	ds_read_b128 v[196:199], v143 offset:22528
	ds_read_b128 v[200:203], v143 offset:23552
	global_load_lds_dwordx4 v[170:171], off
	v_lshl_add_u64 v[220:221], s[22:23], 0, v[132:133]
	s_mov_b32 m0, s45
	s_nop 0
	global_load_lds_dwordx4 v[220:221], off
	s_barrier
	s_waitcnt lgkmcnt(0)
	s_waitcnt lgkmcnt(0)
	v_mfma_f32_16x16x32_bf16 v[62:65], v[144:147], v[160:163], 0
	v_mfma_f32_16x16x32_bf16 v[58:61], v[152:155], v[160:163], 0
	v_mfma_f32_16x16x32_bf16 v[54:57], v[144:147], v[180:183], 0
	v_mfma_f32_16x16x32_bf16 v[50:53], v[152:155], v[180:183], 0
	v_mfma_f32_16x16x32_bf16 v[38:41], v[144:147], v[188:191], 0
	v_mfma_f32_16x16x32_bf16 v[34:37], v[152:155], v[188:191], 0
	v_mfma_f32_16x16x32_bf16 v[22:25], v[144:147], v[196:199], 0
	v_mfma_f32_16x16x32_bf16 v[18:21], v[152:155], v[196:199], 0
	v_mfma_f32_16x16x32_bf16 v[62:65], v[148:151], v[176:179], v[62:65]
	v_mfma_f32_16x16x32_bf16 v[58:61], v[156:159], v[176:179], v[58:61]
	v_mfma_f32_16x16x32_bf16 v[54:57], v[148:151], v[184:187], v[54:57]
	v_mfma_f32_16x16x32_bf16 v[50:53], v[156:159], v[184:187], v[50:53]
	v_mfma_f32_16x16x32_bf16 v[38:41], v[148:151], v[192:195], v[38:41]
	v_mfma_f32_16x16x32_bf16 v[34:37], v[156:159], v[192:195], v[34:37]
	v_mfma_f32_16x16x32_bf16 v[22:25], v[148:151], v[200:203], v[22:25]
	v_mfma_f32_16x16x32_bf16 v[18:21], v[156:159], v[200:203], v[18:21]
	s_barrier
; #define PG8_STAGE(bufoff, gbase, voff) do { _Pragma("unroll") for (int _i = 0; _i < 2; ++_i) \
;         __builtin_amdgcn_global_load_lds((const unsigned*)((const char*)(gbase) + (voff)[_i]), (LAS unsigned*)(lds + (bufoff) + ldsw + _i * 8192), 16, 0, 0); } while (0)
; #define PG8_LDA(dst, b, h) do { _Pragma("unroll") for (int m = 0; m < 4; ++m) _Pragma("unroll") for (int k = 0; k < 2; ++k) dst[m][k] = *(const LAS bf16x8*)(lds + PG8_SA(b, h) + aoff + m * 2048 + k * 1024); } while (0)
; #define PG8_LDB(dst, b, h) do { _Pragma("unroll") for (int n = 0; n < 2; ++n) _Pragma("unroll") for (int k = 0; k < 2; ++k) dst[n][k] = *(const LAS bf16x8*)(lds + PG8_SB(b, h) + boff + n * 2048 + k * 1024); } while (0)
; #define PG8_MMA(ai, bj, At, Bt) do { __builtin_amdgcn_s_setprio(1); _Pragma("unroll") for (int m = 0; m < 4; ++m) _Pragma("unroll") for (int n = 0; n < 2; ++n) _Pragma("unroll") for (int k = 0; k < 2; ++k) \
;         acc[ai][bj][m][n] = __builtin_amdgcn_mfma_f32_16x16x32_bf16(Bt[n][k], At[m][k], acc[ai][bj][m][n], 0, 0, 0); __builtin_amdgcn_s_setprio(0); } while (0)
; #define PG8_WAIT_V(n) asm volatile("s_waitcnt vmcnt(" #n ")" ::: "memory")
; #define PG8_WAIT_L(n) asm volatile("s_waitcnt lgkmcnt(" #n ")" ::: "memory")
; #define PG8_BAR __builtin_amdgcn_s_barrier()
; #define PG8_SCHED __builtin_amdgcn_sched_barrier(0)
; template <class Epi>
; DI void gemm_phase(int wv, LAS unsigned char* lds, const GemmD g, const Epi& E) {
;     ...
;             PG8_STAGE(PG8_SB(0, 1), b2 + hstepB, voffB);
;             PG8_WAIT_V(6); PG8_BAR; PG8_MMA(1, 1, At, B1); PG8_BAR;
;             PG8_LDB(B0, 1, 0); PG8_SCHED; PG8_LDA(At, 1, 0); PG8_STAGE(PG8_SA(0, 1), a2 + hstepA, voffA);
;             PG8_WAIT_L(8); PG8_BAR; PG8_WAIT_L(0); PG8_MMA(0, 0, At, B0); PG8_BAR; PG8_SCHED;
;             PG8_LDB(B1, 1, 1); PG8_STAGE(PG8_SB(1, 0), b3, voffB);
	s_add_u32 s24, s24, s36
	s_addc_u32 s25, s25, 0
	s_add_i32 s2, s2, s37
	v_lshl_add_u64 v[222:223], s[24:25], 0, v[0:1]
	s_mov_b32 m0, s2
	v_lshl_add_u64 v[224:225], s[24:25], 0, v[130:131]
	global_load_lds_dwordx4 v[222:223], off
	s_add_i32 m0, s2, 0x2000
	s_nop 0
	global_load_lds_dwordx4 v[224:225], off
	s_waitcnt vmcnt(6)
	s_barrier
	v_mfma_f32_16x16x32_bf16 v[46:49], v[204:207], v[160:163], 0
	v_mfma_f32_16x16x32_bf16 v[42:45], v[212:215], v[160:163], 0
	v_mfma_f32_16x16x32_bf16 v[30:33], v[204:207], v[180:183], 0
	v_mfma_f32_16x16x32_bf16 v[26:29], v[212:215], v[180:183], 0
	v_mfma_f32_16x16x32_bf16 v[14:17], v[204:207], v[188:191], 0
	v_mfma_f32_16x16x32_bf16 v[10:13], v[212:215], v[188:191], 0
	v_mfma_f32_16x16x32_bf16 v[6:9], v[204:207], v[196:199], 0
	v_mfma_f32_16x16x32_bf16 v[2:5], v[212:215], v[196:199], 0
	v_mfma_f32_16x16x32_bf16 v[46:49], v[208:211], v[176:179], v[46:49]
	v_mfma_f32_16x16x32_bf16 v[42:45], v[216:219], v[176:179], v[42:45]
	v_mfma_f32_16x16x32_bf16 v[30:33], v[208:211], v[184:187], v[30:33]
	v_mfma_f32_16x16x32_bf16 v[26:29], v[216:219], v[184:187], v[26:29]
	v_mfma_f32_16x16x32_bf16 v[14:17], v[208:211], v[192:195], v[14:17]
	v_mfma_f32_16x16x32_bf16 v[10:13], v[216:219], v[192:195], v[10:13]
	v_mfma_f32_16x16x32_bf16 v[6:9], v[208:211], v[200:203], v[6:9]
	v_mfma_f32_16x16x32_bf16 v[2:5], v[216:219], v[200:203], v[2:5]
	s_add_i32 s2, 0, 0x18000
	v_add_u32_e32 v156, s2, v141
	s_barrier
	ds_read_b128 v[144:147], v156
	ds_read_b128 v[148:151], v156 offset:1024
	ds_read_b128 v[152:155], v156 offset:2048
	ds_read_b128 v[156:159], v156 offset:3072
	s_add_u32 s22, s22, 0x40000
	s_addc_u32 s23, s23, 0
	s_mov_b32 m0, s82
	v_lshl_add_u64 v[204:205], s[22:23], 0, v[134:135]
	ds_read_b128 v[160:163], v143 offset:32768
	ds_read_b128 v[176:179], v143 offset:33792
	ds_read_b128 v[180:183], v143 offset:34816
	ds_read_b128 v[184:187], v143 offset:35840
	ds_read_b128 v[188:191], v143 offset:36864
	ds_read_b128 v[192:195], v143 offset:37888
	ds_read_b128 v[196:199], v143 offset:38912
	ds_read_b128 v[200:203], v143 offset:39936
	global_load_lds_dwordx4 v[204:205], off
	v_lshl_add_u64 v[204:205], s[22:23], 0, v[132:133]
	s_mov_b32 m0, s83
	s_nop 0
	global_load_lds_dwordx4 v[204:205], off
	s_waitcnt lgkmcnt(8)
	s_barrier
	s_waitcnt lgkmcnt(0)
	s_waitcnt lgkmcnt(0)
	v_mfma_f32_16x16x32_bf16 v[126:129], v[144:147], v[160:163], v[126:129]
	v_mfma_f32_16x16x32_bf16 v[122:125], v[152:155], v[160:163], v[122:125]
	v_mfma_f32_16x16x32_bf16 v[118:121], v[144:147], v[180:183], v[118:121]
	v_mfma_f32_16x16x32_bf16 v[114:117], v[152:155], v[180:183], v[114:117]
	v_mfma_f32_16x16x32_bf16 v[102:105], v[144:147], v[188:191], v[102:105]
	v_mfma_f32_16x16x32_bf16 v[98:101], v[152:155], v[188:191], v[98:101]
	v_mfma_f32_16x16x32_bf16 v[86:89], v[144:147], v[196:199], v[86:89]
	v_mfma_f32_16x16x32_bf16 v[82:85], v[152:155], v[196:199], v[82:85]
	v_mfma_f32_16x16x32_bf16 v[126:129], v[148:151], v[176:179], v[126:129]
	v_mfma_f32_16x16x32_bf16 v[122:125], v[156:159], v[176:179], v[122:125]
	v_mfma_f32_16x16x32_bf16 v[118:121], v[148:151], v[184:187], v[118:121]
	v_mfma_f32_16x16x32_bf16 v[114:117], v[156:159], v[184:187], v[114:117]
	v_mfma_f32_16x16x32_bf16 v[102:105], v[148:151], v[192:195], v[102:105]
	v_mfma_f32_16x16x32_bf16 v[98:101], v[156:159], v[192:195], v[98:101]
	v_mfma_f32_16x16x32_bf16 v[86:89], v[148:151], v[200:203], v[86:89]
	v_mfma_f32_16x16x32_bf16 v[82:85], v[156:159], v[200:203], v[82:85]
	s_barrier
	s_add_i32 s3, 0, 0x1c000
	s_add_i32 s2, s2, s37
	v_add_u32_e32 v216, s3, v141
	v_lshl_add_u64 v[164:165], v[164:165], 0, s[58:59]
	s_mov_b32 m0, s2
	ds_read_b128 v[204:207], v216
	ds_read_b128 v[208:211], v216 offset:1024
	ds_read_b128 v[212:215], v216 offset:2048
	ds_read_b128 v[216:219], v216 offset:3072
	global_load_lds_dwordx4 v[164:165], off
	v_lshl_add_u64 v[164:165], v[168:169], 0, s[58:59]
	s_add_i32 m0, s2, 0x2000
	s_nop 0
	global_load_lds_dwordx4 v[164:165], off
	s_barrier
; #define PG8_STAGE(bufoff, gbase, voff) do { _Pragma("unroll") for (int _i = 0; _i < 2; ++_i) \
;         __builtin_amdgcn_global_load_lds((const unsigned*)((const char*)(gbase) + (voff)[_i]), (LAS unsigned*)(lds + (bufoff) + ldsw + _i * 8192), 16, 0, 0); } while (0)
; #define PG8_LDA(dst, b, h) do { _Pragma("unroll") for (int m = 0; m < 4; ++m) _Pragma("unroll") for (int k = 0; k < 2; ++k) dst[m][k] = *(const LAS bf16x8*)(lds + PG8_SA(b, h) + aoff + m * 2048 + k * 1024); } while (0)
; #define PG8_MMA(ai, bj, At, Bt) do { __builtin_amdgcn_s_setprio(1); _Pragma("unroll") for (int m = 0; m < 4; ++m) _Pragma("unroll") for (int n = 0; n < 2; ++n) _Pragma("unroll") for (int k = 0; k < 2; ++k) \
;         acc[ai][bj][m][n] = __builtin_amdgcn_mfma_f32_16x16x32_bf16(Bt[n][k], At[m][k], acc[ai][bj][m][n], 0, 0, 0); __builtin_amdgcn_s_setprio(0); } while (0)
; #define PG8_WAIT_V(n) asm volatile("s_waitcnt vmcnt(" #n ")" ::: "memory")
; #define PG8_WAIT_L(n) asm volatile("s_waitcnt lgkmcnt(" #n ")" ::: "memory")
; #define PG8_BAR __builtin_amdgcn_s_barrier()
; #define PG8_SCHED __builtin_amdgcn_sched_barrier(0)
; template <class Epi>
; DI void gemm_phase(int wv, LAS unsigned char* lds, const GemmD g, const Epi& E) {
;     ...
;             PG8_BAR; PG8_WAIT_L(0); PG8_MMA(0, 1, At, B1); PG8_BAR;
;             PG8_LDA(At, 1, 1); PG8_STAGE(PG8_SA(1, 0), a3, voffA);
;             PG8_BAR; PG8_WAIT_L(0); PG8_MMA(1, 0, At, B0); PG8_BAR; PG8_SCHED;
;             PG8_STAGE(PG8_SB(1, 1), b3 + hstepB, voffB);
;             PG8_WAIT_V(6); PG8_BAR; PG8_MMA(1, 1, At, B1); PG8_BAR;
;         }
	s_waitcnt lgkmcnt(0)
	s_waitcnt lgkmcnt(0)
	v_mfma_f32_16x16x32_bf16 v[110:113], v[204:207], v[160:163], v[110:113]
	v_mfma_f32_16x16x32_bf16 v[106:109], v[212:215], v[160:163], v[106:109]
	v_mfma_f32_16x16x32_bf16 v[94:97], v[204:207], v[180:183], v[94:97]
	v_mfma_f32_16x16x32_bf16 v[90:93], v[212:215], v[180:183], v[90:93]
	v_mfma_f32_16x16x32_bf16 v[78:81], v[204:207], v[188:191], v[78:81]
	v_mfma_f32_16x16x32_bf16 v[74:77], v[212:215], v[188:191], v[74:77]
	v_mfma_f32_16x16x32_bf16 v[70:73], v[204:207], v[196:199], v[70:73]
	v_mfma_f32_16x16x32_bf16 v[66:69], v[212:215], v[196:199], v[66:69]
	v_mfma_f32_16x16x32_bf16 v[110:113], v[208:211], v[176:179], v[110:113]
	v_mfma_f32_16x16x32_bf16 v[106:109], v[216:219], v[176:179], v[106:109]
	v_mfma_f32_16x16x32_bf16 v[94:97], v[208:211], v[184:187], v[94:97]
	v_mfma_f32_16x16x32_bf16 v[90:93], v[216:219], v[184:187], v[90:93]
	v_mfma_f32_16x16x32_bf16 v[78:81], v[208:211], v[192:195], v[78:81]
	v_mfma_f32_16x16x32_bf16 v[74:77], v[216:219], v[192:195], v[74:77]
	v_mfma_f32_16x16x32_bf16 v[70:73], v[208:211], v[200:203], v[70:73]
	v_mfma_f32_16x16x32_bf16 v[66:69], v[216:219], v[200:203], v[66:69]
	s_mov_b32 m0, s84
	v_lshl_add_u64 v[164:165], v[170:171], 0, s[58:59]
	s_barrier
	ds_read_b128 v[160:163], v143 offset:49152
	ds_read_b128 v[176:179], v143 offset:50176
	ds_read_b128 v[180:183], v143 offset:51200
	ds_read_b128 v[184:187], v143 offset:52224
	ds_read_b128 v[188:191], v143 offset:53248
	ds_read_b128 v[192:195], v143 offset:54272
	ds_read_b128 v[196:199], v143 offset:55296
	ds_read_b128 v[200:203], v143 offset:56320
	global_load_lds_dwordx4 v[164:165], off
	v_lshl_add_u64 v[164:165], v[220:221], 0, s[58:59]
	s_mov_b32 m0, s85
	s_nop 0
	global_load_lds_dwordx4 v[164:165], off
	s_barrier
	s_waitcnt lgkmcnt(0)
	s_waitcnt lgkmcnt(0)
	v_mfma_f32_16x16x32_bf16 v[62:65], v[144:147], v[160:163], v[62:65]
	v_mfma_f32_16x16x32_bf16 v[58:61], v[152:155], v[160:163], v[58:61]
	v_mfma_f32_16x16x32_bf16 v[54:57], v[144:147], v[180:183], v[54:57]
	v_mfma_f32_16x16x32_bf16 v[50:53], v[152:155], v[180:183], v[50:53]
	v_mfma_f32_16x16x32_bf16 v[38:41], v[144:147], v[188:191], v[38:41]
	v_mfma_f32_16x16x32_bf16 v[34:37], v[152:155], v[188:191], v[34:37]
	v_mfma_f32_16x16x32_bf16 v[22:25], v[144:147], v[196:199], v[22:25]
	v_mfma_f32_16x16x32_bf16 v[18:21], v[152:155], v[196:199], v[18:21]
	v_mfma_f32_16x16x32_bf16 v[62:65], v[148:151], v[176:179], v[62:65]
	v_mfma_f32_16x16x32_bf16 v[58:61], v[156:159], v[176:179], v[58:61]
	v_mfma_f32_16x16x32_bf16 v[54:57], v[148:151], v[184:187], v[54:57]
	v_mfma_f32_16x16x32_bf16 v[50:53], v[156:159], v[184:187], v[50:53]
	v_mfma_f32_16x16x32_bf16 v[38:41], v[148:151], v[192:195], v[38:41]
	v_mfma_f32_16x16x32_bf16 v[34:37], v[156:159], v[192:195], v[34:37]
	v_mfma_f32_16x16x32_bf16 v[22:25], v[148:151], v[200:203], v[22:25]
	v_mfma_f32_16x16x32_bf16 v[18:21], v[156:159], v[200:203], v[18:21]
	s_barrier
	s_add_i32 s2, s3, s37
	v_lshl_add_u64 v[144:145], v[222:223], 0, s[58:59]
	s_mov_b32 m0, s2
	s_nop 0
	global_load_lds_dwordx4 v[144:145], off
	v_lshl_add_u64 v[144:145], v[224:225], 0, s[58:59]
	s_add_i32 m0, s2, 0x2000
	s_nop 0
	global_load_lds_dwordx4 v[144:145], off
	s_waitcnt vmcnt(6)
	s_barrier
	v_mfma_f32_16x16x32_bf16 v[46:49], v[204:207], v[160:163], v[46:49]
	v_mfma_f32_16x16x32_bf16 v[42:45], v[212:215], v[160:163], v[42:45]
	v_mfma_f32_16x16x32_bf16 v[30:33], v[204:207], v[180:183], v[30:33]
	v_mfma_f32_16x16x32_bf16 v[26:29], v[212:215], v[180:183], v[26:29]
	v_mfma_f32_16x16x32_bf16 v[14:17], v[204:207], v[188:191], v[14:17]
	v_mfma_f32_16x16x32_bf16 v[10:13], v[212:215], v[188:191], v[10:13]
	v_mfma_f32_16x16x32_bf16 v[6:9], v[204:207], v[196:199], v[6:9]
	v_mfma_f32_16x16x32_bf16 v[2:5], v[212:215], v[196:199], v[2:5]
	v_mfma_f32_16x16x32_bf16 v[46:49], v[208:211], v[176:179], v[46:49]
	v_mfma_f32_16x16x32_bf16 v[42:45], v[216:219], v[176:179], v[42:45]
	v_mfma_f32_16x16x32_bf16 v[30:33], v[208:211], v[184:187], v[30:33]
	v_mfma_f32_16x16x32_bf16 v[26:29], v[216:219], v[184:187], v[26:29]
	v_mfma_f32_16x16x32_bf16 v[14:17], v[208:211], v[192:195], v[14:17]
	v_mfma_f32_16x16x32_bf16 v[10:13], v[216:219], v[192:195], v[10:13]
	v_mfma_f32_16x16x32_bf16 v[6:9], v[208:211], v[200:203], v[6:9]
	v_mfma_f32_16x16x32_bf16 v[2:5], v[216:219], v[200:203], v[2:5]
	s_add_i32 s95, s95, 2
	s_add_u32 s4, s4, 0x100
	s_addc_u32 s5, s5, 0
	s_add_u32 vcc_hi, vcc_hi, 0x100
	s_addc_u32 s75, s75, 0
	s_cmp_gt_u32 s95, 13
	s_barrier
	s_cbranch_scc0 .LBB0_99
	s_branch .Lgemm_epi_a
	.p2align 6

; #define PG8_STAGE(bufoff, gbase, voff) do { _Pragma("unroll") for (int _i = 0; _i < 2; ++_i) \
;         __builtin_amdgcn_global_load_lds((const unsigned*)((const char*)(gbase) + (voff)[_i]), (LAS unsigned*)(lds + (bufoff) + ldsw + _i * 8192), 16, 0, 0); } while (0)
; #define PG8_LDA(dst, b, h) do { _Pragma("unroll") for (int m = 0; m < 4; ++m) _Pragma("unroll") for (int k = 0; k < 2; ++k) dst[m][k] = *(const LAS bf16x8*)(lds + PG8_SA(b, h) + aoff + m * 2048 + k * 1024); } while (0)
; #define PG8_LDB(dst, b, h) do { _Pragma("unroll") for (int n = 0; n < 2; ++n) _Pragma("unroll") for (int k = 0; k < 2; ++k) dst[n][k] = *(const LAS bf16x8*)(lds + PG8_SB(b, h) + boff + n * 2048 + k * 1024); } while (0)
; #define PG8_MMA(ai, bj, At, Bt) do { __builtin_amdgcn_s_setprio(1); _Pragma("unroll") for (int m = 0; m < 4; ++m) _Pragma("unroll") for (int n = 0; n < 2; ++n) _Pragma("unroll") for (int k = 0; k < 2; ++k) \
;         acc[ai][bj][m][n] = __builtin_amdgcn_mfma_f32_16x16x32_bf16(Bt[n][k], At[m][k], acc[ai][bj][m][n], 0, 0, 0); __builtin_amdgcn_s_setprio(0); } while (0)
; #define PG8_WAIT_L(n) asm volatile("s_waitcnt lgkmcnt(" #n ")" ::: "memory")
; template <class Epi>
; DI void gemm_phase(int wv, LAS unsigned char* lds, const GemmD g, const Epi& E) {
;     ...
;         const bool has_next = S.next(ui + 1, nxt);
;         const char* nA = has_next ? (const char*)g.A + (size_t)nxt.pm * 256 * g.lda * 2 : cA; const char* nB = has_next ? (const char*)g.Bt + PG8_BROW(nxt.pn) * (size_t)g.ldb * 2 : cB;
;         for (int t = 0; t < nt; t += 2) {
;             const bool last = (t == nt - 2);
;             const char* a1 = cA + (size_t)(t + 1) * kstep;
;             const char* a2 = last ? nA : cA + (size_t)(t + 2) * kstep; const char* b2 = last ? nB : cB + (size_t)(t + 2) * kstep;
;             const char* a3 = a2 + kstep; const char* b3 = b2 + kstep;
;             PG8_LDB(B0, 0, 0); PG8_SCHED; PG8_LDA(At, 0, 0); PG8_STAGE(PG8_SA(1, 1), a1 + hstepA, voffA);
;             PG8_WAIT_L(8); PG8_BAR; PG8_WAIT_L(0); PG8_MMA(0, 0, At, B0); PG8_BAR; PG8_SCHED;
;             PG8_LDB(B1, 0, 1); PG8_STAGE(PG8_SB(0, 0), b2, voffB);
;             PG8_BAR; PG8_WAIT_L(0); PG8_MMA(0, 1, At, B1); PG8_BAR;
;             PG8_LDA(At, 0, 1); PG8_STAGE(PG8_SA(0, 0), a2, voffA);
;             PG8_BAR; PG8_WAIT_L(0); PG8_MMA(1, 0, At, B0); PG8_BAR; PG8_SCHED;
.LBB0_489:
	s_ashr_i32 s7, s6, 31
	v_cmp_lt_i64_e32 vcc, s[8:9], v[228:229]
	s_lshl_b64 s[8:9], s[6:7], 19
	s_add_u32 s8, s76, s8
	s_addc_u32 s9, s78, s9
	s_and_b64 s[16:17], vcc, exec
	s_cselect_b32 s7, s9, s27
	s_cselect_b32 s13, s8, s26
	s_lshl_b32 s16, s86, 8
	s_ashr_i32 s17, s16, 31
	s_lshl_b64 s[16:17], s[16:17], 11
	s_add_u32 s22, s39, s16
	s_addc_u32 s23, s40, s17
	s_and_b64 s[16:17], vcc, exec
	s_cselect_b32 s16, s23, s29
	s_cselect_b32 s17, s22, s28
	s_add_u32 s26, s26, 0x40080
	s_addc_u32 s27, s27, 0
	s_add_u32 s36, s28, 0x100
	s_addc_u32 s38, s29, 0
	s_mov_b32 s41, -2
	.p2align 6
	s_add_u32 s2, s26, 0xfffc0080
	s_addc_u32 s3, s27, -1
	s_add_i32 s18, 0, 0x10000
	v_add_u32_e32 v140, s18, v144
	ds_read_b128 v[148:151], v140
	ds_read_b128 v[152:155], v140 offset:1024
	ds_read_b128 v[156:159], v140 offset:2048
	ds_read_b128 v[160:163], v140 offset:3072
	s_cmp_eq_u32 s41, 12
	s_cselect_b32 s31, s7, s3
	s_cselect_b32 s30, s13, s2
	s_cselect_b32 s29, s16, s38
	s_cselect_b32 s28, s17, s36
	v_lshl_add_u64 v[140:141], s[26:27], 0, v[136:137]
	s_add_i32 m0, s25, 0xc000
	ds_read_b128 v[168:171], v146
	ds_read_b128 v[176:179], v146 offset:1024
	ds_read_b128 v[180:183], v146 offset:2048
	ds_read_b128 v[184:187], v146 offset:3072
	ds_read_b128 v[188:191], v146 offset:4096
	ds_read_b128 v[192:195], v146 offset:5120
	ds_read_b128 v[196:199], v146 offset:6144
	ds_read_b128 v[200:203], v146 offset:7168
	global_load_lds_dwordx4 v[140:141], off
	v_lshl_add_u64 v[140:141], s[26:27], 0, v[138:139]
	s_add_i32 m0, s25, 0xe000
	s_nop 0
	global_load_lds_dwordx4 v[140:141], off
	s_waitcnt lgkmcnt(8)
	s_barrier
	s_waitcnt lgkmcnt(0)
	s_waitcnt lgkmcnt(0)
	v_mfma_f32_16x16x32_bf16 v[126:129], v[148:151], v[168:171], 0
	v_mfma_f32_16x16x32_bf16 v[122:125], v[156:159], v[168:171], 0
	v_mfma_f32_16x16x32_bf16 v[110:113], v[148:151], v[180:183], 0
	v_mfma_f32_16x16x32_bf16 v[106:109], v[156:159], v[180:183], 0
	v_mfma_f32_16x16x32_bf16 v[94:97], v[148:151], v[188:191], 0
	v_mfma_f32_16x16x32_bf16 v[90:93], v[156:159], v[188:191], 0
	v_mfma_f32_16x16x32_bf16 v[78:81], v[148:151], v[196:199], 0
	v_mfma_f32_16x16x32_bf16 v[74:77], v[156:159], v[196:199], 0
	v_mfma_f32_16x16x32_bf16 v[126:129], v[152:155], v[176:179], v[126:129]
	v_mfma_f32_16x16x32_bf16 v[122:125], v[160:163], v[176:179], v[122:125]
	v_mfma_f32_16x16x32_bf16 v[110:113], v[152:155], v[184:187], v[110:113]
	v_mfma_f32_16x16x32_bf16 v[106:109], v[160:163], v[184:187], v[106:109]
	v_mfma_f32_16x16x32_bf16 v[94:97], v[152:155], v[192:195], v[94:97]
	v_mfma_f32_16x16x32_bf16 v[90:93], v[160:163], v[192:195], v[90:93]
	v_mfma_f32_16x16x32_bf16 v[78:81], v[152:155], v[200:203], v[78:81]
	v_mfma_f32_16x16x32_bf16 v[74:77], v[160:163], v[200:203], v[74:77]
	s_barrier
	s_add_i32 s2, 0, 0x14000
	v_add_u32_e32 v140, s2, v144
	s_add_i32 s3, s18, s79
	ds_read_b128 v[204:207], v140
	ds_read_b128 v[208:211], v140 offset:1024
	ds_read_b128 v[212:215], v140 offset:2048
	ds_read_b128 v[216:219], v140 offset:3072
	v_lshl_add_u64 v[140:141], s[28:29], 0, v[0:1]
	s_mov_b32 m0, s3
	v_lshl_add_u64 v[164:165], s[28:29], 0, v[134:135]
	global_load_lds_dwordx4 v[140:141], off
	s_add_i32 m0, s3, 0x2000
	s_nop 0
	global_load_lds_dwordx4 v[164:165], off
	s_barrier
	s_waitcnt lgkmcnt(0)
	s_waitcnt lgkmcnt(0)
	v_mfma_f32_16x16x32_bf16 v[118:121], v[204:207], v[168:171], 0
	v_mfma_f32_16x16x32_bf16 v[114:117], v[212:215], v[168:171], 0
	v_mfma_f32_16x16x32_bf16 v[102:105], v[204:207], v[180:183], 0
	v_mfma_f32_16x16x32_bf16 v[98:101], v[212:215], v[180:183], 0
	v_mfma_f32_16x16x32_bf16 v[86:89], v[204:207], v[188:191], 0
	v_mfma_f32_16x16x32_bf16 v[82:85], v[212:215], v[188:191], 0
	v_mfma_f32_16x16x32_bf16 v[70:73], v[204:207], v[196:199], 0
	v_mfma_f32_16x16x32_bf16 v[66:69], v[212:215], v[196:199], 0
	v_mfma_f32_16x16x32_bf16 v[118:121], v[208:211], v[176:179], v[118:121]
	v_mfma_f32_16x16x32_bf16 v[114:117], v[216:219], v[176:179], v[114:117]
	v_mfma_f32_16x16x32_bf16 v[102:105], v[208:211], v[184:187], v[102:105]
	v_mfma_f32_16x16x32_bf16 v[98:101], v[216:219], v[184:187], v[98:101]
	v_mfma_f32_16x16x32_bf16 v[86:89], v[208:211], v[192:195], v[86:89]
	v_mfma_f32_16x16x32_bf16 v[82:85], v[216:219], v[192:195], v[82:85]
	v_mfma_f32_16x16x32_bf16 v[70:73], v[208:211], v[200:203], v[70:73]
	v_mfma_f32_16x16x32_bf16 v[66:69], v[216:219], v[200:203], v[66:69]
	s_mov_b32 m0, s25
	v_lshl_add_u64 v[220:221], s[30:31], 0, v[130:131]
	s_barrier
	ds_read_b128 v[168:171], v146 offset:16384
	ds_read_b128 v[176:179], v146 offset:17408
	ds_read_b128 v[180:183], v146 offset:18432
	ds_read_b128 v[184:187], v146 offset:19456
	ds_read_b128 v[188:191], v146 offset:20480
	ds_read_b128 v[192:195], v146 offset:21504
	ds_read_b128 v[196:199], v146 offset:22528
	ds_read_b128 v[200:203], v146 offset:23552
	global_load_lds_dwordx4 v[220:221], off
	v_lshl_add_u64 v[222:223], s[30:31], 0, v[132:133]
	s_mov_b32 m0, s80
	s_nop 0
	global_load_lds_dwordx4 v[222:223], off
	s_barrier
	s_waitcnt lgkmcnt(0)
	s_waitcnt lgkmcnt(0)
	v_mfma_f32_16x16x32_bf16 v[62:65], v[148:151], v[168:171], 0
	v_mfma_f32_16x16x32_bf16 v[58:61], v[156:159], v[168:171], 0
	v_mfma_f32_16x16x32_bf16 v[46:49], v[148:151], v[180:183], 0
	v_mfma_f32_16x16x32_bf16 v[42:45], v[156:159], v[180:183], 0
	v_mfma_f32_16x16x32_bf16 v[30:33], v[148:151], v[188:191], 0
	v_mfma_f32_16x16x32_bf16 v[26:29], v[156:159], v[188:191], 0
	v_mfma_f32_16x16x32_bf16 v[14:17], v[148:151], v[196:199], 0
	v_mfma_f32_16x16x32_bf16 v[10:13], v[156:159], v[196:199], 0
	v_mfma_f32_16x16x32_bf16 v[62:65], v[152:155], v[176:179], v[62:65]
	v_mfma_f32_16x16x32_bf16 v[58:61], v[160:163], v[176:179], v[58:61]
	v_mfma_f32_16x16x32_bf16 v[46:49], v[152:155], v[184:187], v[46:49]
	v_mfma_f32_16x16x32_bf16 v[42:45], v[160:163], v[184:187], v[42:45]
	v_mfma_f32_16x16x32_bf16 v[30:33], v[152:155], v[192:195], v[30:33]
	v_mfma_f32_16x16x32_bf16 v[26:29], v[160:163], v[192:195], v[26:29]
	v_mfma_f32_16x16x32_bf16 v[14:17], v[152:155], v[200:203], v[14:17]
	v_mfma_f32_16x16x32_bf16 v[10:13], v[160:163], v[200:203], v[10:13]
	s_barrier
; #define PG8_STAGE(bufoff, gbase, voff) do { _Pragma("unroll") for (int _i = 0; _i < 2; ++_i) \
;         __builtin_amdgcn_global_load_lds((const unsigned*)((const char*)(gbase) + (voff)[_i]), (LAS unsigned*)(lds + (bufoff) + ldsw + _i * 8192), 16, 0, 0); } while (0)
; #define PG8_LDA(dst, b, h) do { _Pragma("unroll") for (int m = 0; m < 4; ++m) _Pragma("unroll") for (int k = 0; k < 2; ++k) dst[m][k] = *(const LAS bf16x8*)(lds + PG8_SA(b, h) + aoff + m * 2048 + k * 1024); } while (0)
; #define PG8_LDB(dst, b, h) do { _Pragma("unroll") for (int n = 0; n < 2; ++n) _Pragma("unroll") for (int k = 0; k < 2; ++k) dst[n][k] = *(const LAS bf16x8*)(lds + PG8_SB(b, h) + boff + n * 2048 + k * 1024); } while (0)
; #define PG8_MMA(ai, bj, At, Bt) do { __builtin_amdgcn_s_setprio(1); _Pragma("unroll") for (int m = 0; m < 4; ++m) _Pragma("unroll") for (int n = 0; n < 2; ++n) _Pragma("unroll") for (int k = 0; k < 2; ++k) \
;         acc[ai][bj][m][n] = __builtin_amdgcn_mfma_f32_16x16x32_bf16(Bt[n][k], At[m][k], acc[ai][bj][m][n], 0, 0, 0); __builtin_amdgcn_s_setprio(0); } while (0)
; #define PG8_WAIT_V(n) asm volatile("s_waitcnt vmcnt(" #n ")" ::: "memory")
; #define PG8_WAIT_L(n) asm volatile("s_waitcnt lgkmcnt(" #n ")" ::: "memory")
; #define PG8_BAR __builtin_amdgcn_s_barrier()
; #define PG8_SCHED __builtin_amdgcn_sched_barrier(0)
; template <class Epi>
; DI void gemm_phase(int wv, LAS unsigned char* lds, const GemmD g, const Epi& E) {
;     ...
;             PG8_STAGE(PG8_SB(0, 1), b2 + hstepB, voffB);
;             PG8_WAIT_V(6); PG8_BAR; PG8_MMA(1, 1, At, B1); PG8_BAR;
;             PG8_LDB(B0, 1, 0); PG8_SCHED; PG8_LDA(At, 1, 0); PG8_STAGE(PG8_SA(0, 1), a2 + hstepA, voffA);
;             PG8_WAIT_L(8); PG8_BAR; PG8_WAIT_L(0); PG8_MMA(0, 0, At, B0); PG8_BAR; PG8_SCHED;
;             PG8_LDB(B1, 1, 1); PG8_STAGE(PG8_SB(1, 0), b3, voffB);
	s_add_u32 s18, s28, 0x40000
	s_addc_u32 s19, s29, 0
	s_add_i32 s2, s2, s79
	v_lshl_add_u64 v[148:149], s[18:19], 0, v[0:1]
	s_mov_b32 m0, s2
	s_nop 0
	global_load_lds_dwordx4 v[148:149], off
	v_lshl_add_u64 v[148:149], s[18:19], 0, v[134:135]
	s_add_i32 m0, s2, 0x2000
	s_nop 0
	global_load_lds_dwordx4 v[148:149], off
	s_waitcnt vmcnt(6)
	s_barrier
	v_mfma_f32_16x16x32_bf16 v[54:57], v[204:207], v[168:171], 0
	v_mfma_f32_16x16x32_bf16 v[50:53], v[212:215], v[168:171], 0
	v_mfma_f32_16x16x32_bf16 v[38:41], v[204:207], v[180:183], 0
	v_mfma_f32_16x16x32_bf16 v[34:37], v[212:215], v[180:183], 0
	v_mfma_f32_16x16x32_bf16 v[22:25], v[204:207], v[188:191], 0
	v_mfma_f32_16x16x32_bf16 v[18:21], v[212:215], v[188:191], 0
	v_mfma_f32_16x16x32_bf16 v[6:9], v[204:207], v[196:199], 0
	v_mfma_f32_16x16x32_bf16 v[2:5], v[212:215], v[196:199], 0
	v_mfma_f32_16x16x32_bf16 v[54:57], v[208:211], v[176:179], v[54:57]
	v_mfma_f32_16x16x32_bf16 v[50:53], v[216:219], v[176:179], v[50:53]
	v_mfma_f32_16x16x32_bf16 v[38:41], v[208:211], v[184:187], v[38:41]
	v_mfma_f32_16x16x32_bf16 v[34:37], v[216:219], v[184:187], v[34:37]
	v_mfma_f32_16x16x32_bf16 v[22:25], v[208:211], v[192:195], v[22:25]
	v_mfma_f32_16x16x32_bf16 v[18:21], v[216:219], v[192:195], v[18:21]
	v_mfma_f32_16x16x32_bf16 v[6:9], v[208:211], v[200:203], v[6:9]
	v_mfma_f32_16x16x32_bf16 v[2:5], v[216:219], v[200:203], v[2:5]
	s_add_i32 s2, 0, 0x18000
	v_add_u32_e32 v147, s2, v144
	s_barrier
	ds_read_b128 v[148:151], v147
	ds_read_b128 v[152:155], v147 offset:1024
	ds_read_b128 v[156:159], v147 offset:2048
	ds_read_b128 v[160:163], v147 offset:3072
	s_add_u32 s18, s30, 0x40000
	s_addc_u32 s19, s31, 0
	s_mov_b32 m0, s81
	v_lshl_add_u64 v[204:205], s[18:19], 0, v[130:131]
	ds_read_b128 v[168:171], v146 offset:32768
	ds_read_b128 v[176:179], v146 offset:33792
	ds_read_b128 v[180:183], v146 offset:34816
	ds_read_b128 v[184:187], v146 offset:35840
	ds_read_b128 v[188:191], v146 offset:36864
	ds_read_b128 v[192:195], v146 offset:37888
	ds_read_b128 v[196:199], v146 offset:38912
	ds_read_b128 v[200:203], v146 offset:39936
	global_load_lds_dwordx4 v[204:205], off
	v_lshl_add_u64 v[204:205], s[18:19], 0, v[132:133]
	s_mov_b32 m0, s82
	s_nop 0
	global_load_lds_dwordx4 v[204:205], off
	s_waitcnt lgkmcnt(8)
	s_barrier
	s_waitcnt lgkmcnt(0)
	s_waitcnt lgkmcnt(0)
	v_mfma_f32_16x16x32_bf16 v[126:129], v[148:151], v[168:171], v[126:129]
	v_mfma_f32_16x16x32_bf16 v[122:125], v[156:159], v[168:171], v[122:125]
	v_mfma_f32_16x16x32_bf16 v[110:113], v[148:151], v[180:183], v[110:113]
	v_mfma_f32_16x16x32_bf16 v[106:109], v[156:159], v[180:183], v[106:109]
	v_mfma_f32_16x16x32_bf16 v[94:97], v[148:151], v[188:191], v[94:97]
	v_mfma_f32_16x16x32_bf16 v[90:93], v[156:159], v[188:191], v[90:93]
	v_mfma_f32_16x16x32_bf16 v[78:81], v[148:151], v[196:199], v[78:81]
	v_mfma_f32_16x16x32_bf16 v[74:77], v[156:159], v[196:199], v[74:77]
	v_mfma_f32_16x16x32_bf16 v[126:129], v[152:155], v[176:179], v[126:129]
	v_mfma_f32_16x16x32_bf16 v[122:125], v[160:163], v[176:179], v[122:125]
	v_mfma_f32_16x16x32_bf16 v[110:113], v[152:155], v[184:187], v[110:113]
	v_mfma_f32_16x16x32_bf16 v[106:109], v[160:163], v[184:187], v[106:109]
	v_mfma_f32_16x16x32_bf16 v[94:97], v[152:155], v[192:195], v[94:97]
	v_mfma_f32_16x16x32_bf16 v[90:93], v[160:163], v[192:195], v[90:93]
	v_mfma_f32_16x16x32_bf16 v[78:81], v[152:155], v[200:203], v[78:81]
	v_mfma_f32_16x16x32_bf16 v[74:77], v[160:163], v[200:203], v[74:77]
	s_barrier
	s_add_i32 s3, 0, 0x1c000
	s_add_i32 s2, s2, s79
	v_add_u32_e32 v147, s3, v144
	v_lshl_add_u64 v[140:141], v[140:141], 0, s[58:59]
	s_mov_b32 m0, s2
	ds_read_b128 v[204:207], v147
	ds_read_b128 v[208:211], v147 offset:1024
	ds_read_b128 v[212:215], v147 offset:2048
	ds_read_b128 v[216:219], v147 offset:3072
	global_load_lds_dwordx4 v[140:141], off
	v_lshl_add_u64 v[140:141], v[164:165], 0, s[58:59]
	s_add_i32 m0, s2, 0x2000
	s_nop 0
	global_load_lds_dwordx4 v[140:141], off
	s_barrier
; #define PG8_STAGE(bufoff, gbase, voff) do { _Pragma("unroll") for (int _i = 0; _i < 2; ++_i) \
;         __builtin_amdgcn_global_load_lds((const unsigned*)((const char*)(gbase) + (voff)[_i]), (LAS unsigned*)(lds + (bufoff) + ldsw + _i * 8192), 16, 0, 0); } while (0)
; #define PG8_LDA(dst, b, h) do { _Pragma("unroll") for (int m = 0; m < 4; ++m) _Pragma("unroll") for (int k = 0; k < 2; ++k) dst[m][k] = *(const LAS bf16x8*)(lds + PG8_SA(b, h) + aoff + m * 2048 + k * 1024); } while (0)
; #define PG8_MMA(ai, bj, At, Bt) do { __builtin_amdgcn_s_setprio(1); _Pragma("unroll") for (int m = 0; m < 4; ++m) _Pragma("unroll") for (int n = 0; n < 2; ++n) _Pragma("unroll") for (int k = 0; k < 2; ++k) \
;         acc[ai][bj][m][n] = __builtin_amdgcn_mfma_f32_16x16x32_bf16(Bt[n][k], At[m][k], acc[ai][bj][m][n], 0, 0, 0); __builtin_amdgcn_s_setprio(0); } while (0)
; #define PG8_WAIT_V(n) asm volatile("s_waitcnt vmcnt(" #n ")" ::: "memory")
; #define PG8_WAIT_L(n) asm volatile("s_waitcnt lgkmcnt(" #n ")" ::: "memory")
; #define PG8_BAR __builtin_amdgcn_s_barrier()
; #define PG8_SCHED __builtin_amdgcn_sched_barrier(0)
; template <class Epi>
; DI void gemm_phase(int wv, LAS unsigned char* lds, const GemmD g, const Epi& E) {
;     ...
;             PG8_BAR; PG8_WAIT_L(0); PG8_MMA(0, 1, At, B1); PG8_BAR;
;             PG8_LDA(At, 1, 1); PG8_STAGE(PG8_SA(1, 0), a3, voffA);
;             PG8_BAR; PG8_WAIT_L(0); PG8_MMA(1, 0, At, B0); PG8_BAR; PG8_SCHED;
;             PG8_STAGE(PG8_SB(1, 1), b3 + hstepB, voffB);
;             PG8_WAIT_V(6); PG8_BAR; PG8_MMA(1, 1, At, B1); PG8_BAR;
;         }
	s_waitcnt lgkmcnt(0)
	s_waitcnt lgkmcnt(0)
	v_mfma_f32_16x16x32_bf16 v[118:121], v[204:207], v[168:171], v[118:121]
	v_mfma_f32_16x16x32_bf16 v[114:117], v[212:215], v[168:171], v[114:117]
	v_mfma_f32_16x16x32_bf16 v[102:105], v[204:207], v[180:183], v[102:105]
	v_mfma_f32_16x16x32_bf16 v[98:101], v[212:215], v[180:183], v[98:101]
	v_mfma_f32_16x16x32_bf16 v[86:89], v[204:207], v[188:191], v[86:89]
	v_mfma_f32_16x16x32_bf16 v[82:85], v[212:215], v[188:191], v[82:85]
	v_mfma_f32_16x16x32_bf16 v[70:73], v[204:207], v[196:199], v[70:73]
	v_mfma_f32_16x16x32_bf16 v[66:69], v[212:215], v[196:199], v[66:69]
	v_mfma_f32_16x16x32_bf16 v[118:121], v[208:211], v[176:179], v[118:121]
	v_mfma_f32_16x16x32_bf16 v[114:117], v[216:219], v[176:179], v[114:117]
	v_mfma_f32_16x16x32_bf16 v[102:105], v[208:211], v[184:187], v[102:105]
	v_mfma_f32_16x16x32_bf16 v[98:101], v[216:219], v[184:187], v[98:101]
	v_mfma_f32_16x16x32_bf16 v[86:89], v[208:211], v[192:195], v[86:89]
	v_mfma_f32_16x16x32_bf16 v[82:85], v[216:219], v[192:195], v[82:85]
	v_mfma_f32_16x16x32_bf16 v[70:73], v[208:211], v[200:203], v[70:73]
	v_mfma_f32_16x16x32_bf16 v[66:69], v[216:219], v[200:203], v[66:69]
	s_mov_b32 m0, s83
	v_lshl_add_u64 v[140:141], v[220:221], 0, s[58:59]
	s_barrier
	ds_read_b128 v[168:171], v146 offset:49152
	ds_read_b128 v[176:179], v146 offset:50176
	ds_read_b128 v[180:183], v146 offset:51200
	ds_read_b128 v[184:187], v146 offset:52224
	ds_read_b128 v[188:191], v146 offset:53248
	ds_read_b128 v[192:195], v146 offset:54272
	ds_read_b128 v[196:199], v146 offset:55296
	ds_read_b128 v[200:203], v146 offset:56320
	global_load_lds_dwordx4 v[140:141], off
	v_lshl_add_u64 v[140:141], v[222:223], 0, s[58:59]
	s_mov_b32 m0, s84
	s_nop 0
	global_load_lds_dwordx4 v[140:141], off
	s_barrier
	s_waitcnt lgkmcnt(0)
	s_waitcnt lgkmcnt(0)
	v_mfma_f32_16x16x32_bf16 v[62:65], v[148:151], v[168:171], v[62:65]
	v_mfma_f32_16x16x32_bf16 v[58:61], v[156:159], v[168:171], v[58:61]
	v_mfma_f32_16x16x32_bf16 v[46:49], v[148:151], v[180:183], v[46:49]
	v_mfma_f32_16x16x32_bf16 v[42:45], v[156:159], v[180:183], v[42:45]
	v_mfma_f32_16x16x32_bf16 v[30:33], v[148:151], v[188:191], v[30:33]
	v_mfma_f32_16x16x32_bf16 v[26:29], v[156:159], v[188:191], v[26:29]
	v_mfma_f32_16x16x32_bf16 v[14:17], v[148:151], v[196:199], v[14:17]
	v_mfma_f32_16x16x32_bf16 v[10:13], v[156:159], v[196:199], v[10:13]
	v_mfma_f32_16x16x32_bf16 v[62:65], v[152:155], v[176:179], v[62:65]
	v_mfma_f32_16x16x32_bf16 v[58:61], v[160:163], v[176:179], v[58:61]
	v_mfma_f32_16x16x32_bf16 v[46:49], v[152:155], v[184:187], v[46:49]
	v_mfma_f32_16x16x32_bf16 v[42:45], v[160:163], v[184:187], v[42:45]
	v_mfma_f32_16x16x32_bf16 v[30:33], v[152:155], v[192:195], v[30:33]
	v_mfma_f32_16x16x32_bf16 v[26:29], v[160:163], v[192:195], v[26:29]
	v_mfma_f32_16x16x32_bf16 v[14:17], v[152:155], v[200:203], v[14:17]
	v_mfma_f32_16x16x32_bf16 v[10:13], v[160:163], v[200:203], v[10:13]
	s_barrier
	s_add_u32 s18, s28, 0x40080
	s_addc_u32 s19, s29, 0
	s_add_i32 s2, s3, s79
	v_lshl_add_u64 v[140:141], s[18:19], 0, v[0:1]
	s_mov_b32 m0, s2
	s_nop 0
	global_load_lds_dwordx4 v[140:141], off
	v_lshl_add_u64 v[140:141], s[18:19], 0, v[134:135]
	s_add_i32 m0, s2, 0x2000
	s_nop 0
	global_load_lds_dwordx4 v[140:141], off
	s_waitcnt vmcnt(6)
	s_barrier
	v_mfma_f32_16x16x32_bf16 v[54:57], v[204:207], v[168:171], v[54:57]
	v_mfma_f32_16x16x32_bf16 v[50:53], v[212:215], v[168:171], v[50:53]
	v_mfma_f32_16x16x32_bf16 v[38:41], v[204:207], v[180:183], v[38:41]
	v_mfma_f32_16x16x32_bf16 v[34:37], v[212:215], v[180:183], v[34:37]
	v_mfma_f32_16x16x32_bf16 v[22:25], v[204:207], v[188:191], v[22:25]
	v_mfma_f32_16x16x32_bf16 v[18:21], v[212:215], v[188:191], v[18:21]
	v_mfma_f32_16x16x32_bf16 v[6:9], v[204:207], v[196:199], v[6:9]
	v_mfma_f32_16x16x32_bf16 v[2:5], v[212:215], v[196:199], v[2:5]
	v_mfma_f32_16x16x32_bf16 v[54:57], v[208:211], v[176:179], v[54:57]
	v_mfma_f32_16x16x32_bf16 v[50:53], v[216:219], v[176:179], v[50:53]
	v_mfma_f32_16x16x32_bf16 v[38:41], v[208:211], v[184:187], v[38:41]
	v_mfma_f32_16x16x32_bf16 v[34:37], v[216:219], v[184:187], v[34:37]
	v_mfma_f32_16x16x32_bf16 v[22:25], v[208:211], v[192:195], v[22:25]
	v_mfma_f32_16x16x32_bf16 v[18:21], v[216:219], v[192:195], v[18:21]
	v_mfma_f32_16x16x32_bf16 v[6:9], v[208:211], v[200:203], v[6:9]
	v_mfma_f32_16x16x32_bf16 v[2:5], v[216:219], v[200:203], v[2:5]
	s_add_i32 s41, s41, 2
	s_add_u32 s26, s26, 0x100
	s_addc_u32 s27, s27, 0
	s_add_u32 s36, s36, 0x100
	s_addc_u32 s38, s38, 0
	s_cmp_gt_u32 s41, 13
	s_barrier
	s_cbranch_scc0 .LBB0_490
	s_branch .Lgemm_epi_b
	.p2align 6

; #define PG8_STAGE(bufoff, gbase, voff) do { _Pragma("unroll") for (int _i = 0; _i < 2; ++_i) \
;         __builtin_amdgcn_global_load_lds((const unsigned*)((const char*)(gbase) + (voff)[_i]), (LAS unsigned*)(lds + (bufoff) + ldsw + _i * 8192), 16, 0, 0); } while (0)
; #define PG8_LDA(dst, b, h) do { _Pragma("unroll") for (int m = 0; m < 4; ++m) _Pragma("unroll") for (int k = 0; k < 2; ++k) dst[m][k] = *(const LAS bf16x8*)(lds + PG8_SA(b, h) + aoff + m * 2048 + k * 1024); } while (0)
; #define PG8_LDB(dst, b, h) do { _Pragma("unroll") for (int n = 0; n < 2; ++n) _Pragma("unroll") for (int k = 0; k < 2; ++k) dst[n][k] = *(const LAS bf16x8*)(lds + PG8_SB(b, h) + boff + n * 2048 + k * 1024); } while (0)
; #define PG8_MMA(ai, bj, At, Bt) do { __builtin_amdgcn_s_setprio(1); _Pragma("unroll") for (int m = 0; m < 4; ++m) _Pragma("unroll") for (int n = 0; n < 2; ++n) _Pragma("unroll") for (int k = 0; k < 2; ++k) \
;         acc[ai][bj][m][n] = __builtin_amdgcn_mfma_f32_16x16x32_bf16(Bt[n][k], At[m][k], acc[ai][bj][m][n], 0, 0, 0); __builtin_amdgcn_s_setprio(0); } while (0)
; #define PG8_WAIT_L(n) asm volatile("s_waitcnt lgkmcnt(" #n ")" ::: "memory")
; template <class Epi>
; DI void gemm_phase(int wv, LAS unsigned char* lds, const GemmD g, const Epi& E) {
;     ...
;         const bool has_next = S.next(ui + 1, nxt);
;         const char* nA = has_next ? (const char*)g.A + (size_t)nxt.pm * 256 * g.lda * 2 : cA; const char* nB = has_next ? (const char*)g.Bt + PG8_BROW(nxt.pn) * (size_t)g.ldb * 2 : cB;
;         for (int t = 0; t < nt; t += 2) {
;             const bool last = (t == nt - 2);
;             const char* a1 = cA + (size_t)(t + 1) * kstep;
;             const char* a2 = last ? nA : cA + (size_t)(t + 2) * kstep; const char* b2 = last ? nB : cB + (size_t)(t + 2) * kstep;
;             const char* a3 = a2 + kstep; const char* b3 = b2 + kstep;
;             PG8_LDB(B0, 0, 0); PG8_SCHED; PG8_LDA(At, 0, 0); PG8_STAGE(PG8_SA(1, 1), a1 + hstepA, voffA);
;             PG8_WAIT_L(8); PG8_BAR; PG8_WAIT_L(0); PG8_MMA(0, 0, At, B0); PG8_BAR; PG8_SCHED;
;             PG8_LDB(B1, 0, 1); PG8_STAGE(PG8_SB(0, 0), b2, voffB);
;             PG8_BAR; PG8_WAIT_L(0); PG8_MMA(0, 1, At, B1); PG8_BAR;
;             PG8_LDA(At, 0, 1); PG8_STAGE(PG8_SA(0, 0), a2, voffA);
;             PG8_BAR; PG8_WAIT_L(0); PG8_MMA(1, 0, At, B0); PG8_BAR; PG8_SCHED;
.LBB0_543:
	s_ashr_i32 s23, s22, 31
	s_lshl_b64 s[18:19], s[22:23], s85
	v_cmp_lt_i64_e32 vcc, s[24:25], v[174:175]
	s_add_u32 s24, s81, s18
	s_addc_u32 s25, s80, s19
	s_and_b64 s[18:19], vcc, exec
	s_cselect_b32 s23, s25, s29
	s_cselect_b32 s68, s24, s28
	s_lshl_b32 s18, s55, 8
	s_ashr_i32 s19, s18, 31
	s_lshl_b64 s[18:19], s[18:19], s9
	s_add_u32 s26, s82, s18
	s_addc_u32 s27, s83, s19
	s_and_b64 s[18:19], vcc, exec
	s_cselect_b32 vcc_lo, s27, s31
	s_cselect_b32 vcc_hi, s26, s30
	s_add_u32 s28, s28, 0x80
	s_addc_u32 s29, s29, 0
	s_add_u32 s37, s30, 0x100
	s_addc_u32 s18, s31, 0
	s_mov_b32 s19, 0
	.p2align 6
	s_add_i32 s95, s19, 2
	s_add_u32 s2, s28, 0x80
	s_addc_u32 s3, s29, 0
	s_add_i32 s94, 0, 0x10000
	v_add_u32_e32 v145, s94, v141
	ds_read_b128 v[146:149], v145
	ds_read_b128 v[150:153], v145 offset:1024
	ds_read_b128 v[154:157], v145 offset:2048
	ds_read_b128 v[158:161], v145 offset:3072
	s_cmp_eq_u32 s17, s19
	s_cselect_b32 s31, s23, s3
	s_cselect_b32 s30, s68, s2
	s_cselect_b32 s35, vcc_lo, s18
	s_cselect_b32 s34, vcc_hi, s37
	v_lshl_add_u64 v[200:201], s[28:29], 0, v[136:137]
	s_add_i32 m0, s86, 0xc000
	ds_read_b128 v[162:165], v144
	ds_read_b128 v[168:171], v144 offset:1024
	ds_read_b128 v[176:179], v144 offset:2048
	ds_read_b128 v[180:183], v144 offset:3072
	ds_read_b128 v[184:187], v144 offset:4096
	ds_read_b128 v[188:191], v144 offset:5120
	ds_read_b128 v[192:195], v144 offset:6144
	ds_read_b128 v[196:199], v144 offset:7168
	global_load_lds_dwordx4 v[200:201], off
	v_lshl_add_u64 v[200:201], s[28:29], 0, v[138:139]
	s_add_i32 m0, s86, 0xe000
	s_nop 0
	global_load_lds_dwordx4 v[200:201], off
	s_waitcnt lgkmcnt(8)
	s_barrier
	s_waitcnt lgkmcnt(0)
	s_waitcnt lgkmcnt(0)
	v_mfma_f32_16x16x32_bf16 v[126:129], v[146:149], v[162:165], 0
	v_mfma_f32_16x16x32_bf16 v[122:125], v[154:157], v[162:165], 0
	v_mfma_f32_16x16x32_bf16 v[118:121], v[146:149], v[176:179], 0
	v_mfma_f32_16x16x32_bf16 v[114:117], v[154:157], v[176:179], 0
	v_mfma_f32_16x16x32_bf16 v[102:105], v[146:149], v[184:187], 0
	v_mfma_f32_16x16x32_bf16 v[98:101], v[154:157], v[184:187], 0
	v_mfma_f32_16x16x32_bf16 v[86:89], v[146:149], v[192:195], 0
	v_mfma_f32_16x16x32_bf16 v[82:85], v[154:157], v[192:195], 0
	v_mfma_f32_16x16x32_bf16 v[126:129], v[150:153], v[168:171], v[126:129]
	v_mfma_f32_16x16x32_bf16 v[122:125], v[158:161], v[168:171], v[122:125]
	v_mfma_f32_16x16x32_bf16 v[118:121], v[150:153], v[180:183], v[118:121]
	v_mfma_f32_16x16x32_bf16 v[114:117], v[158:161], v[180:183], v[114:117]
	v_mfma_f32_16x16x32_bf16 v[102:105], v[150:153], v[188:191], v[102:105]
	v_mfma_f32_16x16x32_bf16 v[98:101], v[158:161], v[188:191], v[98:101]
	v_mfma_f32_16x16x32_bf16 v[86:89], v[150:153], v[196:199], v[86:89]
	v_mfma_f32_16x16x32_bf16 v[82:85], v[158:161], v[196:199], v[82:85]
	s_barrier
	s_add_i32 s2, 0, 0x14000
	s_add_i32 s3, s94, s84
	v_add_u32_e32 v145, s2, v141
	v_lshl_add_u64 v[216:217], s[34:35], 0, v[0:1]
	s_mov_b32 m0, s3
	ds_read_b128 v[200:203], v145
	ds_read_b128 v[204:207], v145 offset:1024
	ds_read_b128 v[208:211], v145 offset:2048
	ds_read_b128 v[212:215], v145 offset:3072
	global_load_lds_dwordx4 v[216:217], off
	v_lshl_add_u64 v[218:219], s[34:35], 0, v[134:135]
	s_add_i32 m0, s3, 0x2000
	s_nop 0
	global_load_lds_dwordx4 v[218:219], off
	s_barrier
	s_waitcnt lgkmcnt(0)
	s_waitcnt lgkmcnt(0)
	v_mfma_f32_16x16x32_bf16 v[110:113], v[200:203], v[162:165], 0
	v_mfma_f32_16x16x32_bf16 v[106:109], v[208:211], v[162:165], 0
	v_mfma_f32_16x16x32_bf16 v[94:97], v[200:203], v[176:179], 0
	v_mfma_f32_16x16x32_bf16 v[90:93], v[208:211], v[176:179], 0
	v_mfma_f32_16x16x32_bf16 v[78:81], v[200:203], v[184:187], 0
	v_mfma_f32_16x16x32_bf16 v[74:77], v[208:211], v[184:187], 0
	v_mfma_f32_16x16x32_bf16 v[70:73], v[200:203], v[192:195], 0
	v_mfma_f32_16x16x32_bf16 v[66:69], v[208:211], v[192:195], 0
	v_mfma_f32_16x16x32_bf16 v[110:113], v[204:207], v[168:171], v[110:113]
	v_mfma_f32_16x16x32_bf16 v[106:109], v[212:215], v[168:171], v[106:109]
	v_mfma_f32_16x16x32_bf16 v[94:97], v[204:207], v[180:183], v[94:97]
	v_mfma_f32_16x16x32_bf16 v[90:93], v[212:215], v[180:183], v[90:93]
	v_mfma_f32_16x16x32_bf16 v[78:81], v[204:207], v[188:191], v[78:81]
	v_mfma_f32_16x16x32_bf16 v[74:77], v[212:215], v[188:191], v[74:77]
	v_mfma_f32_16x16x32_bf16 v[70:73], v[204:207], v[196:199], v[70:73]
	v_mfma_f32_16x16x32_bf16 v[66:69], v[212:215], v[196:199], v[66:69]
	s_mov_b32 m0, s86
	v_lshl_add_u64 v[220:221], s[30:31], 0, v[130:131]
	s_barrier
	ds_read_b128 v[162:165], v144 offset:16384
	ds_read_b128 v[168:171], v144 offset:17408
	ds_read_b128 v[176:179], v144 offset:18432
	ds_read_b128 v[180:183], v144 offset:19456
	ds_read_b128 v[184:187], v144 offset:20480
	ds_read_b128 v[188:191], v144 offset:21504
	ds_read_b128 v[192:195], v144 offset:22528
	ds_read_b128 v[196:199], v144 offset:23552
	global_load_lds_dwordx4 v[220:221], off
	v_lshl_add_u64 v[222:223], s[30:31], 0, v[132:133]
	s_mov_b32 m0, s87
	s_nop 0
	global_load_lds_dwordx4 v[222:223], off
	s_barrier
	s_waitcnt lgkmcnt(0)
	s_waitcnt lgkmcnt(0)
	v_mfma_f32_16x16x32_bf16 v[62:65], v[146:149], v[162:165], 0
	v_mfma_f32_16x16x32_bf16 v[58:61], v[154:157], v[162:165], 0
	v_mfma_f32_16x16x32_bf16 v[54:57], v[146:149], v[176:179], 0
	v_mfma_f32_16x16x32_bf16 v[50:53], v[154:157], v[176:179], 0
	v_mfma_f32_16x16x32_bf16 v[38:41], v[146:149], v[184:187], 0
	v_mfma_f32_16x16x32_bf16 v[34:37], v[154:157], v[184:187], 0
	v_mfma_f32_16x16x32_bf16 v[22:25], v[146:149], v[192:195], 0
	v_mfma_f32_16x16x32_bf16 v[18:21], v[154:157], v[192:195], 0
	v_mfma_f32_16x16x32_bf16 v[62:65], v[150:153], v[168:171], v[62:65]
	v_mfma_f32_16x16x32_bf16 v[58:61], v[158:161], v[168:171], v[58:61]
	v_mfma_f32_16x16x32_bf16 v[54:57], v[150:153], v[180:183], v[54:57]
	v_mfma_f32_16x16x32_bf16 v[50:53], v[158:161], v[180:183], v[50:53]
	v_mfma_f32_16x16x32_bf16 v[38:41], v[150:153], v[188:191], v[38:41]
	v_mfma_f32_16x16x32_bf16 v[34:37], v[158:161], v[188:191], v[34:37]
	v_mfma_f32_16x16x32_bf16 v[22:25], v[150:153], v[196:199], v[22:25]
	v_mfma_f32_16x16x32_bf16 v[18:21], v[158:161], v[196:199], v[18:21]
	s_barrier
; #define PG8_STAGE(bufoff, gbase, voff) do { _Pragma("unroll") for (int _i = 0; _i < 2; ++_i) \
;         __builtin_amdgcn_global_load_lds((const unsigned*)((const char*)(gbase) + (voff)[_i]), (LAS unsigned*)(lds + (bufoff) + ldsw + _i * 8192), 16, 0, 0); } while (0)
; #define PG8_LDA(dst, b, h) do { _Pragma("unroll") for (int m = 0; m < 4; ++m) _Pragma("unroll") for (int k = 0; k < 2; ++k) dst[m][k] = *(const LAS bf16x8*)(lds + PG8_SA(b, h) + aoff + m * 2048 + k * 1024); } while (0)
; #define PG8_LDB(dst, b, h) do { _Pragma("unroll") for (int n = 0; n < 2; ++n) _Pragma("unroll") for (int k = 0; k < 2; ++k) dst[n][k] = *(const LAS bf16x8*)(lds + PG8_SB(b, h) + boff + n * 2048 + k * 1024); } while (0)
; #define PG8_MMA(ai, bj, At, Bt) do { __builtin_amdgcn_s_setprio(1); _Pragma("unroll") for (int m = 0; m < 4; ++m) _Pragma("unroll") for (int n = 0; n < 2; ++n) _Pragma("unroll") for (int k = 0; k < 2; ++k) \
;         acc[ai][bj][m][n] = __builtin_amdgcn_mfma_f32_16x16x32_bf16(Bt[n][k], At[m][k], acc[ai][bj][m][n], 0, 0, 0); __builtin_amdgcn_s_setprio(0); } while (0)
; #define PG8_WAIT_V(n) asm volatile("s_waitcnt vmcnt(" #n ")" ::: "memory")
; #define PG8_WAIT_L(n) asm volatile("s_waitcnt lgkmcnt(" #n ")" ::: "memory")
; #define PG8_BAR __builtin_amdgcn_s_barrier()
; #define PG8_SCHED __builtin_amdgcn_sched_barrier(0)
; template <class Epi>
; DI void gemm_phase(int wv, LAS unsigned char* lds, const GemmD g, const Epi& E) {
;     ...
;             PG8_STAGE(PG8_SB(0, 1), b2 + hstepB, voffB);
;             PG8_WAIT_V(6); PG8_BAR; PG8_MMA(1, 1, At, B1); PG8_BAR;
;             PG8_LDB(B0, 1, 0); PG8_SCHED; PG8_LDA(At, 1, 0); PG8_STAGE(PG8_SA(0, 1), a2 + hstepA, voffA);
;             PG8_WAIT_L(8); PG8_BAR; PG8_WAIT_L(0); PG8_MMA(0, 0, At, B0); PG8_BAR; PG8_SCHED;
;             PG8_LDB(B1, 1, 1); PG8_STAGE(PG8_SB(1, 0), b3, voffB);
	s_add_u32 s34, s34, s56
	s_addc_u32 s35, s35, 0
	s_add_i32 s2, s2, s84
	v_lshl_add_u64 v[224:225], s[34:35], 0, v[0:1]
	s_mov_b32 m0, s2
	v_lshl_add_u64 v[226:227], s[34:35], 0, v[134:135]
	global_load_lds_dwordx4 v[224:225], off
	s_add_i32 m0, s2, 0x2000
	s_nop 0
	global_load_lds_dwordx4 v[226:227], off
	s_waitcnt vmcnt(6)
	s_barrier
	v_mfma_f32_16x16x32_bf16 v[46:49], v[200:203], v[162:165], 0
	v_mfma_f32_16x16x32_bf16 v[42:45], v[208:211], v[162:165], 0
	v_mfma_f32_16x16x32_bf16 v[30:33], v[200:203], v[176:179], 0
	v_mfma_f32_16x16x32_bf16 v[26:29], v[208:211], v[176:179], 0
	v_mfma_f32_16x16x32_bf16 v[14:17], v[200:203], v[184:187], 0
	v_mfma_f32_16x16x32_bf16 v[10:13], v[208:211], v[184:187], 0
	v_mfma_f32_16x16x32_bf16 v[6:9], v[200:203], v[192:195], 0
	v_mfma_f32_16x16x32_bf16 v[2:5], v[208:211], v[192:195], 0
	v_mfma_f32_16x16x32_bf16 v[46:49], v[204:207], v[168:171], v[46:49]
	v_mfma_f32_16x16x32_bf16 v[42:45], v[212:215], v[168:171], v[42:45]
	v_mfma_f32_16x16x32_bf16 v[30:33], v[204:207], v[180:183], v[30:33]
	v_mfma_f32_16x16x32_bf16 v[26:29], v[212:215], v[180:183], v[26:29]
	v_mfma_f32_16x16x32_bf16 v[14:17], v[204:207], v[188:191], v[14:17]
	v_mfma_f32_16x16x32_bf16 v[10:13], v[212:215], v[188:191], v[10:13]
	v_mfma_f32_16x16x32_bf16 v[6:9], v[204:207], v[196:199], v[6:9]
	v_mfma_f32_16x16x32_bf16 v[2:5], v[212:215], v[196:199], v[2:5]
	s_add_i32 s2, 0, 0x18000
	v_add_u32_e32 v145, s2, v141
	s_barrier
	ds_read_b128 v[146:149], v145
	ds_read_b128 v[150:153], v145 offset:1024
	ds_read_b128 v[154:157], v145 offset:2048
	ds_read_b128 v[158:161], v145 offset:3072
	s_add_u32 s30, s30, s56
	s_addc_u32 s31, s31, 0
	s_mov_b32 m0, s74
	v_lshl_add_u64 v[200:201], s[30:31], 0, v[130:131]
	ds_read_b128 v[162:165], v144 offset:32768
	ds_read_b128 v[168:171], v144 offset:33792
	ds_read_b128 v[176:179], v144 offset:34816
	ds_read_b128 v[180:183], v144 offset:35840
	ds_read_b128 v[184:187], v144 offset:36864
	ds_read_b128 v[188:191], v144 offset:37888
	ds_read_b128 v[192:195], v144 offset:38912
	ds_read_b128 v[196:199], v144 offset:39936
	global_load_lds_dwordx4 v[200:201], off
	v_lshl_add_u64 v[200:201], s[30:31], 0, v[132:133]
	s_mov_b32 m0, s41
	s_nop 0
	global_load_lds_dwordx4 v[200:201], off
	s_waitcnt lgkmcnt(8)
	s_barrier
	s_waitcnt lgkmcnt(0)
	s_waitcnt lgkmcnt(0)
	v_mfma_f32_16x16x32_bf16 v[126:129], v[146:149], v[162:165], v[126:129]
	v_mfma_f32_16x16x32_bf16 v[122:125], v[154:157], v[162:165], v[122:125]
	v_mfma_f32_16x16x32_bf16 v[118:121], v[146:149], v[176:179], v[118:121]
	v_mfma_f32_16x16x32_bf16 v[114:117], v[154:157], v[176:179], v[114:117]
	v_mfma_f32_16x16x32_bf16 v[102:105], v[146:149], v[184:187], v[102:105]
	v_mfma_f32_16x16x32_bf16 v[98:101], v[154:157], v[184:187], v[98:101]
	v_mfma_f32_16x16x32_bf16 v[86:89], v[146:149], v[192:195], v[86:89]
	v_mfma_f32_16x16x32_bf16 v[82:85], v[154:157], v[192:195], v[82:85]
	v_mfma_f32_16x16x32_bf16 v[126:129], v[150:153], v[168:171], v[126:129]
	v_mfma_f32_16x16x32_bf16 v[122:125], v[158:161], v[168:171], v[122:125]
	v_mfma_f32_16x16x32_bf16 v[118:121], v[150:153], v[180:183], v[118:121]
	v_mfma_f32_16x16x32_bf16 v[114:117], v[158:161], v[180:183], v[114:117]
	v_mfma_f32_16x16x32_bf16 v[102:105], v[150:153], v[188:191], v[102:105]
	v_mfma_f32_16x16x32_bf16 v[98:101], v[158:161], v[188:191], v[98:101]
	v_mfma_f32_16x16x32_bf16 v[86:89], v[150:153], v[196:199], v[86:89]
	v_mfma_f32_16x16x32_bf16 v[82:85], v[158:161], v[196:199], v[82:85]
	s_barrier
	s_add_i32 s3, 0, 0x1c000
	s_add_i32 s2, s2, s84
	v_add_u32_e32 v145, s3, v141
	v_lshl_add_u64 v[216:217], v[216:217], 0, s[58:59]
	s_mov_b32 m0, s2
	ds_read_b128 v[200:203], v145
	ds_read_b128 v[204:207], v145 offset:1024
	ds_read_b128 v[208:211], v145 offset:2048
	ds_read_b128 v[212:215], v145 offset:3072
	global_load_lds_dwordx4 v[216:217], off
	v_lshl_add_u64 v[216:217], v[218:219], 0, s[58:59]
	s_add_i32 m0, s2, 0x2000
	s_nop 0
	global_load_lds_dwordx4 v[216:217], off
	s_barrier
; #define PG8_STAGE(bufoff, gbase, voff) do { _Pragma("unroll") for (int _i = 0; _i < 2; ++_i) \
;         __builtin_amdgcn_global_load_lds((const unsigned*)((const char*)(gbase) + (voff)[_i]), (LAS unsigned*)(lds + (bufoff) + ldsw + _i * 8192), 16, 0, 0); } while (0)
; #define PG8_LDA(dst, b, h) do { _Pragma("unroll") for (int m = 0; m < 4; ++m) _Pragma("unroll") for (int k = 0; k < 2; ++k) dst[m][k] = *(const LAS bf16x8*)(lds + PG8_SA(b, h) + aoff + m * 2048 + k * 1024); } while (0)
; #define PG8_MMA(ai, bj, At, Bt) do { __builtin_amdgcn_s_setprio(1); _Pragma("unroll") for (int m = 0; m < 4; ++m) _Pragma("unroll") for (int n = 0; n < 2; ++n) _Pragma("unroll") for (int k = 0; k < 2; ++k) \
;         acc[ai][bj][m][n] = __builtin_amdgcn_mfma_f32_16x16x32_bf16(Bt[n][k], At[m][k], acc[ai][bj][m][n], 0, 0, 0); __builtin_amdgcn_s_setprio(0); } while (0)
; #define PG8_WAIT_V(n) asm volatile("s_waitcnt vmcnt(" #n ")" ::: "memory")
; #define PG8_WAIT_L(n) asm volatile("s_waitcnt lgkmcnt(" #n ")" ::: "memory")
; #define PG8_BAR __builtin_amdgcn_s_barrier()
; #define PG8_SCHED __builtin_amdgcn_sched_barrier(0)
; template <class Epi>
; DI void gemm_phase(int wv, LAS unsigned char* lds, const GemmD g, const Epi& E) {
;     ...
;             PG8_BAR; PG8_WAIT_L(0); PG8_MMA(0, 1, At, B1); PG8_BAR;
;             PG8_LDA(At, 1, 1); PG8_STAGE(PG8_SA(1, 0), a3, voffA);
;             PG8_BAR; PG8_WAIT_L(0); PG8_MMA(1, 0, At, B0); PG8_BAR; PG8_SCHED;
;             PG8_STAGE(PG8_SB(1, 1), b3 + hstepB, voffB);
;             PG8_WAIT_V(6); PG8_BAR; PG8_MMA(1, 1, At, B1); PG8_BAR;
;         }
	s_waitcnt lgkmcnt(0)
	s_waitcnt lgkmcnt(0)
	v_mfma_f32_16x16x32_bf16 v[110:113], v[200:203], v[162:165], v[110:113]
	v_mfma_f32_16x16x32_bf16 v[106:109], v[208:211], v[162:165], v[106:109]
	v_mfma_f32_16x16x32_bf16 v[94:97], v[200:203], v[176:179], v[94:97]
	v_mfma_f32_16x16x32_bf16 v[90:93], v[208:211], v[176:179], v[90:93]
	v_mfma_f32_16x16x32_bf16 v[78:81], v[200:203], v[184:187], v[78:81]
	v_mfma_f32_16x16x32_bf16 v[74:77], v[208:211], v[184:187], v[74:77]
	v_mfma_f32_16x16x32_bf16 v[70:73], v[200:203], v[192:195], v[70:73]
	v_mfma_f32_16x16x32_bf16 v[66:69], v[208:211], v[192:195], v[66:69]
	v_mfma_f32_16x16x32_bf16 v[110:113], v[204:207], v[168:171], v[110:113]
	v_mfma_f32_16x16x32_bf16 v[106:109], v[212:215], v[168:171], v[106:109]
	v_mfma_f32_16x16x32_bf16 v[94:97], v[204:207], v[180:183], v[94:97]
	v_mfma_f32_16x16x32_bf16 v[90:93], v[212:215], v[180:183], v[90:93]
	v_mfma_f32_16x16x32_bf16 v[78:81], v[204:207], v[188:191], v[78:81]
	v_mfma_f32_16x16x32_bf16 v[74:77], v[212:215], v[188:191], v[74:77]
	v_mfma_f32_16x16x32_bf16 v[70:73], v[204:207], v[196:199], v[70:73]
	v_mfma_f32_16x16x32_bf16 v[66:69], v[212:215], v[196:199], v[66:69]
	s_mov_b32 m0, s13
	v_lshl_add_u64 v[216:217], v[220:221], 0, s[58:59]
	s_barrier
	ds_read_b128 v[162:165], v144 offset:49152
	ds_read_b128 v[168:171], v144 offset:50176
	ds_read_b128 v[176:179], v144 offset:51200
	ds_read_b128 v[180:183], v144 offset:52224
	ds_read_b128 v[184:187], v144 offset:53248
	ds_read_b128 v[188:191], v144 offset:54272
	ds_read_b128 v[192:195], v144 offset:55296
	ds_read_b128 v[196:199], v144 offset:56320
	global_load_lds_dwordx4 v[216:217], off
	v_lshl_add_u64 v[216:217], v[222:223], 0, s[58:59]
	s_mov_b32 m0, s16
	s_nop 0
	global_load_lds_dwordx4 v[216:217], off
	s_barrier
	s_waitcnt lgkmcnt(0)
	s_waitcnt lgkmcnt(0)
	v_mfma_f32_16x16x32_bf16 v[62:65], v[146:149], v[162:165], v[62:65]
	v_mfma_f32_16x16x32_bf16 v[58:61], v[154:157], v[162:165], v[58:61]
	v_mfma_f32_16x16x32_bf16 v[54:57], v[146:149], v[176:179], v[54:57]
	v_mfma_f32_16x16x32_bf16 v[50:53], v[154:157], v[176:179], v[50:53]
	v_mfma_f32_16x16x32_bf16 v[38:41], v[146:149], v[184:187], v[38:41]
	v_mfma_f32_16x16x32_bf16 v[34:37], v[154:157], v[184:187], v[34:37]
	v_mfma_f32_16x16x32_bf16 v[22:25], v[146:149], v[192:195], v[22:25]
	v_mfma_f32_16x16x32_bf16 v[18:21], v[154:157], v[192:195], v[18:21]
	v_mfma_f32_16x16x32_bf16 v[62:65], v[150:153], v[168:171], v[62:65]
	v_mfma_f32_16x16x32_bf16 v[58:61], v[158:161], v[168:171], v[58:61]
	v_mfma_f32_16x16x32_bf16 v[54:57], v[150:153], v[180:183], v[54:57]
	v_mfma_f32_16x16x32_bf16 v[50:53], v[158:161], v[180:183], v[50:53]
	v_mfma_f32_16x16x32_bf16 v[38:41], v[150:153], v[188:191], v[38:41]
	v_mfma_f32_16x16x32_bf16 v[34:37], v[158:161], v[188:191], v[34:37]
	v_mfma_f32_16x16x32_bf16 v[22:25], v[150:153], v[196:199], v[22:25]
	v_mfma_f32_16x16x32_bf16 v[18:21], v[158:161], v[196:199], v[18:21]
	s_barrier
	s_add_i32 s2, s3, s84
	v_lshl_add_u64 v[146:147], v[224:225], 0, s[58:59]
	s_mov_b32 m0, s2
	s_nop 0
	global_load_lds_dwordx4 v[146:147], off
	v_lshl_add_u64 v[146:147], v[226:227], 0, s[58:59]
	s_add_i32 m0, s2, 0x2000
	s_nop 0
	global_load_lds_dwordx4 v[146:147], off
	s_waitcnt vmcnt(6)
	s_barrier
	v_mfma_f32_16x16x32_bf16 v[46:49], v[200:203], v[162:165], v[46:49]
	v_mfma_f32_16x16x32_bf16 v[42:45], v[208:211], v[162:165], v[42:45]
	v_mfma_f32_16x16x32_bf16 v[30:33], v[200:203], v[176:179], v[30:33]
	v_mfma_f32_16x16x32_bf16 v[26:29], v[208:211], v[176:179], v[26:29]
	v_mfma_f32_16x16x32_bf16 v[14:17], v[200:203], v[184:187], v[14:17]
	v_mfma_f32_16x16x32_bf16 v[10:13], v[208:211], v[184:187], v[10:13]
	v_mfma_f32_16x16x32_bf16 v[6:9], v[200:203], v[192:195], v[6:9]
	v_mfma_f32_16x16x32_bf16 v[2:5], v[208:211], v[192:195], v[2:5]
	v_mfma_f32_16x16x32_bf16 v[46:49], v[204:207], v[168:171], v[46:49]
	v_mfma_f32_16x16x32_bf16 v[42:45], v[212:215], v[168:171], v[42:45]
	v_mfma_f32_16x16x32_bf16 v[30:33], v[204:207], v[180:183], v[30:33]
	v_mfma_f32_16x16x32_bf16 v[26:29], v[212:215], v[180:183], v[26:29]
	v_mfma_f32_16x16x32_bf16 v[14:17], v[204:207], v[188:191], v[14:17]
	v_mfma_f32_16x16x32_bf16 v[10:13], v[212:215], v[188:191], v[10:13]
	v_mfma_f32_16x16x32_bf16 v[6:9], v[204:207], v[196:199], v[6:9]
	v_mfma_f32_16x16x32_bf16 v[2:5], v[212:215], v[196:199], v[2:5]
	s_add_u32 s28, s28, 0x100
	s_addc_u32 s29, s29, 0
	s_add_u32 s37, s37, 0x100
	s_addc_u32 s18, s18, 0
	s_cmp_ge_u32 s95, s38
	s_mov_b32 s19, s95
	s_barrier
	s_cbranch_scc0 .LBB0_544
	s_branch .Lgemm_epi_c
	.p2align 6
